# v4: attention LDS-DMA ring + tile reschedule + fused linear-bias MFMAs with resident fragments; phase C stage-0 loads issued together
# speedup vs baseline: 1.0147x; 1.0043x over previous
; __device__ __forceinline__ float bflo(unsigned w) { return __uint_as_float(w << 16); }
; __device__ __forceinline__ float bfhi(unsigned w) { return __uint_as_float(w & 0xffff0000u); }
; #define LAS __attribute__((address_space(3)))
; __device__ __forceinline__ float bflo(unsigned w) { return __uint_as_float(w << 16); }
; __device__ __forceinline__ float bfhi(unsigned w) { return __uint_as_float(w & 0xffff0000u); }
; #define a_log INP(5)
; #define dt_bias INP(6)
; __device__ __forceinline__ void gdn_prep_unit(LAS unsigned char* lds, unsigned char* ws, const float* conv_w, const float* a_log, const float* dt_bias,
;                                               int l, int Tp, int ci, int h, int nci, int nh, unsigned& pre_ba, int tid, int wave, int lane) {
;     ...
;     const int row0 = ci * 64, tin = row0 % Tp; const bool first = (tin == 0), last = (tin + 64 == Tp);
;     LAS float* BETA = (LAS float*)(lds + D1_BETA); LAS float* GC = (LAS float*)(lds + D1_GC);
;     if (tid < 128) {
;         const int d = tid >> 6, r = tid & 63, c = d ? 63 - r : r;
;         const float braw = bflo(pre_ba), araw = bfhi(pre_ba);
;         if (nci >= 0) { const bf16* pn = PROJ + (size_t)(nci * 64 + c) * LDP + C_BA; pre_ba = (unsigned)pn[d * 8 + nh] | ((unsigned)pn[16 + d * 8 + nh] << 16); }
;         const float beta = __builtin_amdgcn_rcpf(1.0f + __expf(-braw));
;         const float x = araw + dt_bias[(l * 2 + d) * 8 + h];
;         const float sp = fmaxf(x, 0.f) + log1pf(__expf(-fabsf(x)));
;         float gcv = -__expf(a_log[(l * 2 + d) * 8 + h]) * sp;
.LBB0_320:
	s_mov_b32 s4, s6
	s_add_i32 s6, s6, s69
	s_ashr_i32 s80, s4, 3
	s_and_b32 s7, s4, 7
	s_cmpk_lt_i32 s6, 0x800
	s_cselect_b64 s[30:31], -1, 0
	s_cmpk_gt_i32 s6, 0x7ff
	s_cselect_b64 s[76:77], -1, 0
	s_and_saveexec_b64 s[26:27], s[38:39]
	s_cbranch_execz .LBB0_326
	v_or_b32_e32 v6, s7, v202
	v_readlane_b32 s4, v254, 38
	v_readlane_b32 s5, v254, 39
	v_ashrrev_i32_e32 v7, 31, v6
	v_lshlrev_b64 v[6:7], 2, v[6:7]
	v_lshl_add_u64 v[10:11], s[4:5], 0, v[6:7]
	v_readlane_b32 s4, v254, 36
	v_readlane_b32 s5, v254, 37
	global_load_dword v242, v[10:11], off
	s_nop 0
	v_lshl_add_u64 v[10:11], s[4:5], 0, v[6:7]
	global_load_dword v243, v[10:11], off
	s_ashr_i32 s4, s6, 3
	s_and_b64 s[16:17], s[30:31], exec
	s_cselect_b32 s16, s4, -1
	s_max_i32 s16, s16, 0
	v_mov_b32_e32 v8, v210
	v_lshl_or_b32 v8, s16, 6, v105
	v_mov_b64_e32 v[6:7], s[50:51]
	s_and_b32 s4, s6, 7
	v_mad_u64_u32 v[6:7], s[16:17], v8, s70, v[6:7]
	s_mov_b64 s[16:17], 0x8400
	v_or_b32_e32 v8, s4, v104
	v_lshl_add_u64 v[6:7], v[6:7], 0, s[16:17]
	v_ashrrev_i32_e32 v9, 31, v8
	v_lshl_add_u64 v[8:9], v[8:9], 1, v[6:7]
	global_load_ushort v240, v[8:9], off
	v_or_b32_e32 v8, s4, v107
	v_ashrrev_i32_e32 v9, 31, v8
	v_lshl_add_u64 v[6:7], v[8:9], 1, v[6:7]
	global_load_ushort v241, v[6:7], off
; __device__ __forceinline__ float bflo(unsigned w) { return __uint_as_float(w << 16); }
; __device__ __forceinline__ float bfhi(unsigned w) { return __uint_as_float(w & 0xffff0000u); }
; __device__ __forceinline__ float bflo(unsigned w) { return __uint_as_float(w << 16); }
; __device__ __forceinline__ float bfhi(unsigned w) { return __uint_as_float(w & 0xffff0000u); }
; #define a_log INP(5)
; #define dt_bias INP(6)
; __device__ __forceinline__ void gdn_prep_unit(LAS unsigned char* lds, unsigned char* ws, const float* conv_w, const float* a_log, const float* dt_bias,
;                                               int l, int Tp, int ci, int h, int nci, int nh, unsigned& pre_ba, int tid, int wave, int lane) {
;     ...
;         const float braw = bflo(pre_ba), araw = bfhi(pre_ba);
;         if (nci >= 0) { const bf16* pn = PROJ + (size_t)(nci * 64 + c) * LDP + C_BA; pre_ba = (unsigned)pn[d * 8 + nh] | ((unsigned)pn[16 + d * 8 + nh] << 16); }
;         const float beta = __builtin_amdgcn_rcpf(1.0f + __expf(-braw));
;         const float x = araw + dt_bias[(l * 2 + d) * 8 + h];
;         const float sp = fmaxf(x, 0.f) + log1pf(__expf(-fabsf(x)));
;         float gcv = -__expf(a_log[(l * 2 + d) * 8 + h]) * sp;
; #pragma unroll
;         for (int off = 1; off < 64; off <<= 1) { const float t = __shfl_up(gcv, off); if (r >= off) gcv += t; }
;         BETA[d * 64 + r] = beta; GC[d * 64 + r] = gcv;
;         if (r == 63) *(float*)(gdn_rec(ws, d, ci, h) + REC_GAM) = __expf(gcv);
.LBB0_323:
	v_lshlrev_b32_e32 v6, 16, v210
	v_mul_f32_e32 v6, 0xbfb8aa3b, v6
	v_exp_f32_e32 v6, v6
	v_readlane_b32 s4, v254, 38
	v_readlane_b32 s5, v254, 39
	v_and_b32_e32 v12, 0xffff0000, v210
	v_add_f32_e32 v9, 1.0, v6
	v_or_b32_e32 v6, s7, v202
	v_ashrrev_i32_e32 v7, 31, v6
	v_lshlrev_b64 v[6:7], 2, v[6:7]
	v_lshl_add_u64 v[10:11], s[4:5], 0, v[6:7]
	s_mov_b32 s3, 0xbfb8aa3b
	s_mov_b32 s4, 0x3f2aaaab
	v_rcp_f32_e32 v9, v9
	s_waitcnt vmcnt(3)
	v_add_f32_e32 v10, v242, v12
	v_max_f32_e32 v12, 0, v10
	v_mul_f32_e64 v10, |v10|, s3
	v_exp_f32_e32 v13, v10
	s_mov_b32 s3, 0x7f800000
	v_add_f32_e32 v14, 1.0, v13
	v_add_f32_e32 v10, -1.0, v14
	v_sub_f32_e32 v11, v10, v14
	v_add_f32_e32 v11, 1.0, v11
	v_sub_f32_e32 v10, v13, v10
	v_add_f32_e32 v15, v10, v11
	v_frexp_mant_f32_e32 v10, v14
	v_cmp_gt_f32_e32 vcc, s4, v10
	v_cvt_f64_f32_e32 v[10:11], v14
	v_frexp_exp_i32_f64_e32 v10, v[10:11]
	v_subbrev_co_u32_e32 v10, vcc, 0, v10, vcc
	v_sub_u32_e32 v11, 0, v10
	v_ldexp_f32 v14, v14, v11
	v_ldexp_f32 v11, v15, v11
	v_add_f32_e32 v15, -1.0, v14
	v_add_f32_e32 v16, 1.0, v15
	v_sub_f32_e32 v16, v14, v16
	v_add_f32_e32 v16, v11, v16
	v_add_f32_e32 v17, v15, v16
	v_sub_f32_e32 v15, v17, v15
	v_sub_f32_e32 v15, v16, v15
	v_add_f32_e32 v16, 1.0, v14
	v_add_f32_e32 v18, -1.0, v16
	v_sub_f32_e32 v14, v14, v18
	v_add_f32_e32 v11, v11, v14
	v_add_f32_e32 v14, v16, v11
	v_sub_f32_e32 v16, v14, v16
	v_sub_f32_e32 v11, v11, v16
	v_rcp_f32_e32 v16, v14
	v_cvt_f32_i32_e32 v10, v10
	s_mov_b32 s4, 0x3f317218
	v_cmp_neq_f32_e32 vcc, s3, v13
	v_mul_f32_e32 v18, v17, v16
	v_mul_f32_e32 v19, v14, v18
	v_fma_f32 v20, v18, v14, -v19
	v_fmac_f32_e32 v20, v18, v11
	v_add_f32_e32 v21, v19, v20
	v_sub_f32_e32 v22, v17, v21
	v_sub_f32_e32 v17, v17, v22
	v_sub_f32_e32 v19, v21, v19
	v_sub_f32_e32 v17, v17, v21
	v_add_f32_e32 v15, v15, v17
	v_sub_f32_e32 v17, v19, v20
	v_add_f32_e32 v15, v17, v15
	v_add_f32_e32 v17, v22, v15
	v_mul_f32_e32 v19, v16, v17
	v_mul_f32_e32 v20, v14, v19
	v_fma_f32 v14, v19, v14, -v20
	v_fmac_f32_e32 v14, v19, v11
	v_sub_f32_e32 v11, v22, v17
	v_add_f32_e32 v11, v15, v11
	v_add_f32_e32 v15, v20, v14
	v_sub_f32_e32 v21, v17, v15
	v_sub_f32_e32 v17, v17, v21
	v_sub_f32_e32 v20, v15, v20
	v_sub_f32_e32 v15, v17, v15
	v_add_f32_e32 v11, v11, v15
	v_sub_f32_e32 v14, v20, v14
	v_add_f32_e32 v11, v14, v11
	v_add_f32_e32 v14, v18, v19
	v_add_f32_e32 v11, v21, v11
	v_sub_f32_e32 v15, v14, v18
	v_mul_f32_e32 v11, v16, v11
	v_sub_f32_e32 v15, v19, v15
	v_add_f32_e32 v11, v15, v11
	v_mul_f32_e32 v18, 0x3f317218, v10
	v_add_f32_e32 v15, v14, v11
	v_fma_f32 v19, v10, s4, -v18
	v_mul_f32_e32 v16, v15, v15
	v_mov_b32_e32 v17, 0x3ecc95a3
	v_fmac_f32_e32 v19, 0xb102e308, v10
	v_sub_f32_e32 v10, v15, v14
	v_fmamk_f32 v17, v16, 0x3e9b6dac, v17
	v_sub_f32_e32 v10, v11, v10
	v_add_f32_e32 v11, v18, v19
	v_fmaak_f32 v17, v16, v17, 0x3f2aaada
	v_sub_f32_e32 v14, v11, v18
	v_ldexp_f32 v18, v15, 1
	v_mul_f32_e32 v15, v15, v16
	v_mul_f32_e32 v15, v15, v17
	v_add_f32_e32 v16, v18, v15
	v_sub_f32_e32 v17, v16, v18
	v_ldexp_f32 v10, v10, 1
	v_sub_f32_e32 v15, v15, v17
	v_add_f32_e32 v10, v10, v15
	v_add_f32_e32 v15, v16, v10
	v_sub_f32_e32 v16, v15, v16
	v_sub_f32_e32 v10, v10, v16
	v_add_f32_e32 v16, v11, v15
	v_sub_f32_e32 v17, v16, v11
	v_sub_f32_e32 v18, v16, v17
	v_sub_f32_e32 v14, v19, v14
	v_sub_f32_e32 v11, v11, v18
	v_sub_f32_e32 v15, v15, v17
	v_add_f32_e32 v11, v15, v11
	v_add_f32_e32 v15, v14, v10
	v_sub_f32_e32 v17, v15, v14
	v_sub_f32_e32 v18, v15, v17
	v_sub_f32_e32 v14, v14, v18
	v_sub_f32_e32 v10, v10, v17
	v_add_f32_e32 v11, v15, v11
	v_add_f32_e32 v10, v10, v14
	v_add_f32_e32 v14, v16, v11
	v_sub_f32_e32 v15, v14, v16
	v_sub_f32_e32 v11, v11, v15
	v_add_f32_e32 v10, v10, v11
	v_add_f32_e32 v10, v14, v10
	v_cndmask_b32_e32 v10, v225, v10, vcc
	v_cmp_ngt_f32_e32 vcc, -1.0, v13
	s_mov_b32 s4, 0x33800000
	s_nop 0
	v_cndmask_b32_e32 v10, v226, v10, vcc
	v_cmp_neq_f32_e32 vcc, -1.0, v13
	s_nop 1
	v_cndmask_b32_e32 v10, v227, v10, vcc
	v_cmp_lt_f32_e64 vcc, |v13|, s4
	v_readlane_b32 s4, v254, 36
	v_readlane_b32 s5, v254, 37
	v_cndmask_b32_e32 v10, v10, v13, vcc
	v_add_f32_e32 v10, v12, v10
	v_lshl_add_u64 v[6:7], s[4:5], 0, v[6:7]
	v_add_u32_e32 v12, -1, v224
	v_readlane_b32 s4, v254, 40
	v_readlane_b32 s5, v254, 41
	s_waitcnt vmcnt(2)
	v_mul_f32_e32 v6, 0x3fb8aa3b, v243
	v_exp_f32_e32 v7, v6
	v_and_b32_e32 v6, 64, v224
	v_cmp_lt_i32_e32 vcc, v12, v6
	v_mul_f32_e64 v11, v10, -v7
	s_nop 0
	v_cndmask_b32_e32 v12, v12, v224, vcc
	v_lshlrev_b32_e32 v12, 2, v12
	ds_bpermute_b32 v12, v12, v11
	s_waitcnt lgkmcnt(0)
	v_fma_f32 v7, v10, -v7, v12
	v_add_u32_e32 v10, -2, v224
	v_cmp_lt_i32_e32 vcc, v10, v6
	v_cndmask_b32_e64 v7, v7, v11, s[4:5]
	v_readlane_b32 s4, v254, 42
	v_cndmask_b32_e32 v10, v10, v224, vcc
	v_lshlrev_b32_e32 v10, 2, v10
	ds_bpermute_b32 v10, v10, v7
	v_readlane_b32 s5, v254, 43
	s_waitcnt lgkmcnt(0)
	v_add_f32_e32 v10, v7, v10
	v_cndmask_b32_e64 v7, v10, v7, s[4:5]
	v_add_u32_e32 v10, -4, v224
	v_cmp_lt_i32_e32 vcc, v10, v6
	v_readlane_b32 s4, v254, 44
	v_readlane_b32 s5, v254, 45
	v_cndmask_b32_e32 v10, v10, v224, vcc
	v_lshlrev_b32_e32 v10, 2, v10
	ds_bpermute_b32 v10, v10, v7
	s_waitcnt lgkmcnt(0)
	v_add_f32_e32 v10, v7, v10
	v_cndmask_b32_e64 v7, v10, v7, s[4:5]
	v_add_u32_e32 v10, -8, v224
	v_cmp_lt_i32_e32 vcc, v10, v6
	v_readlane_b32 s4, v254, 46
	v_readlane_b32 s5, v254, 47
	v_cndmask_b32_e32 v10, v10, v224, vcc
	v_lshlrev_b32_e32 v10, 2, v10
	ds_bpermute_b32 v10, v10, v7
	s_waitcnt lgkmcnt(0)
	v_add_f32_e32 v10, v7, v10
	v_cndmask_b32_e64 v7, v10, v7, s[4:5]
	v_add_u32_e32 v10, -16, v224
	v_cmp_lt_i32_e32 vcc, v10, v6
	v_readlane_b32 s4, v254, 48
	v_readlane_b32 s5, v254, 49
	v_cndmask_b32_e32 v10, v10, v224, vcc
	v_lshlrev_b32_e32 v10, 2, v10
	ds_bpermute_b32 v10, v10, v7
	s_waitcnt lgkmcnt(0)
	v_add_f32_e32 v10, v7, v10
	v_cndmask_b32_e64 v7, v10, v7, s[4:5]
	v_subrev_u32_e32 v10, 32, v224
	v_cmp_lt_i32_e32 vcc, v10, v6
	v_readlane_b32 s4, v254, 50
	v_readlane_b32 s5, v254, 51
	v_cndmask_b32_e32 v6, v10, v224, vcc
	v_lshlrev_b32_e32 v6, 2, v6
	ds_bpermute_b32 v6, v6, v7
	s_waitcnt lgkmcnt(0)
	v_add_f32_e32 v6, v7, v6
	v_cndmask_b32_e64 v7, v6, v7, s[4:5]
	v_readlane_b32 s4, v254, 54
	v_readlane_b32 s5, v254, 55
	ds_write_b32 v108, v9
	ds_write_b32 v109, v7
	s_waitcnt vmcnt(0)
	v_lshl_or_b32 v8, v241, 16, v240
	s_and_saveexec_b64 s[30:31], s[4:5]
	s_cbranch_execz .LBB0_325
	v_mul_f32_e32 v6, 0x3fb8aa3b, v6
	s_ashr_i32 s81, s80, 31
	v_exp_f32_e32 v9, v6
	v_lshl_add_u64 v[6:7], s[80:81], 3, v[2:3]
	v_or_b32_e32 v6, s7, v6
	v_mov_b64_e32 v[10:11], s[42:43]
	s_mov_b32 s3, 0x12000
	v_mad_u64_u32 v[10:11], s[16:17], v6, s3, v[10:11]
	v_mad_i32_i24 v7, v7, s3, v11
	v_add_co_u32_e32 v6, vcc, 0x4d60c000, v10
	s_nop 1
	v_addc_co_u32_e32 v7, vcc, 0, v7, vcc
	global_store_dword v[6:7], v9, off offset:2048

; #define LAS __attribute__((address_space(3)))
; __device__ __forceinline__ unsigned cvtpk(float lo, float hi) { const f32x2_t v = {lo, hi}; const bf16x2_t b = __builtin_convertvector(v, bf16x2_t); return __builtin_bit_cast(unsigned, b); }
; #define SLOAD(S, k0) do { S.vs0 = *(const v4u*)(Vg + (size_t)((k0) + sr) * LDP); S.vs1 = *(const v4u*)(Vg + (size_t)((k0) + 32 + sr) * LDP); \
;         if (MODE) { S.ks0 = *(const v4u*)(Kg + (size_t)(k0) * LDP); } \
;         else { S.ks0 = *(const v4u*)(Kg + (size_t)((k0) + sr) * LDP); S.ks1 = *(const v4u*)(Kg + (size_t)((k0) + 32 + sr) * LDP); } } while (0)
; template <int MODE, bool FIXED>
; __device__ __forceinline__ void attn_unit(LAS unsigned char* lds, unsigned char* ws, const AttnParams& P, int l, int Tp, int sq, int h, int qb, int part, int np, int pslot, int tid, int wave, int lane) {
;     ...
;         const bf16* Vg = PROJ + (size_t)seq0 * LDP + vcol + sc;
;         const bf16* Kg = MODE ? PROJ + (size_t)(seq0 + kr1) * LDP + kcol + mp * 64 + kc1 : PROJ + (size_t)seq0 * LDP + kcol + sc;
;         constexpr int DEPTH = 1;
;         struct Stg { v4u vs0, vs1, ks0, ks1; };
;         Stg sA, sB;
;     ...
;         if (MODE == 1 && tid < 64) {
;             const unsigned one2 = 0x3F803F80u, cw = cvtpk((float)tid, (float)tid);
;             *(LAS v4u*)(K_lds + 8192 + tid * 32) = (v4u){one2, cw, 0u, 0u}; *(LAS v4u*)(K_lds + 8192 + tid * 32 + 16) = (v4u){0u, 0u, 0u, 0u}; }
;         if (jlo < jhi) SLOAD(sA, jlo * 64);
.LBB0_931:
	s_or_b64 exec, exec, s[10:11]
	s_lshl_b32 s10, s26, 6
	s_lshl_b32 s60, s10, 1
	v_lshl_add_u64 v[186:187], v[174:175], 0, s[60:61]
	s_and_saveexec_b64 s[10:11], s[8:9]
	s_cbranch_execz .LBB0_933
	v_readfirstlane_b32 s100, v168
	v_readfirstlane_b32 s101, v188
	s_lshl_b32 s73, s31, 11
	s_mov_b32 s53, 0
	s_add_i32 s101, s101, -1
	v_and_b32_e32 v113, 63, v0
	v_bfe_u32 v110, v113, 2, 3
	v_and_b32_e32 v111, 3, v110
	v_lshrrev_b32_e32 v110, 2, v110
	v_lshl_or_b32 v110, v110, 3, v111
	s_lshr_b32 s3, s31, 1
	s_lshl_b32 s3, s3, 4
	s_and_b32 s32, s31, 1
	s_lshl_b32 s32, s32, 2
	s_add_i32 s3, s3, s32
	v_add_u32_e32 v110, s3, v110
	v_and_b32_e32 v111, 15, v0
	v_lshlrev_b32_e32 v111, 4, v111
	v_sub_co_u32_e64 v108, s[98:99], v172, v111
	s_nop 1
	v_subbrev_co_u32_e64 v109, s[98:99], 0, v173, s[98:99]
	v_mad_i64_i32 v[102:103], s[98:99], v110, s70, v[108:109]
	v_and_b32_e32 v111, 3, v113
	v_lshlrev_b32_e32 v111, 4, v111
	v_lshrrev_b32_e32 v110, 5, v113
	v_lshl_or_b32 v110, v110, 6, v111
	v_mov_b32_e32 v111, 0
	v_lshl_add_u64 v[102:103], v[102:103], 0, v[110:111]
	v_and_b32_e32 v110, 7, v0
	v_lshlrev_b32_e32 v110, 4, v110
	v_bfe_u32 v112, v0, 4, 3
	v_lshlrev_b32_e32 v112, 4, v112
	v_xor_b32_e32 v112, v110, v112
	v_sub_co_u32_e64 v104, s[98:99], v186, v110
	s_nop 1
	v_subbrev_co_u32_e64 v105, s[98:99], 0, v187, s[98:99]
	v_mov_b32_e32 v113, 0
	v_lshl_add_u64 v[104:105], v[104:105], 0, v[112:113]
	v_and_b32_e32 v113, 31, v0
	v_cvt_f32_u32_e32 v112, v113
	v_add_u32_e32 v113, 32, v113
	v_cvt_pk_bf16_f32 v111, v112, v112
	v_cvt_f32_u32_e32 v112, v113
	v_and_b32_e32 v113, 32, v0
	v_cvt_pk_bf16_f32 v177, v112, v112
	v_cmp_eq_u32_e64 s[98:99], 0, v113
	v_mov_b32_e32 v110, 0x3f803f80
	v_mov_b32_e32 v112, 0
	v_cndmask_b32_e64 v110, 0, v110, s[98:99]
	v_cndmask_b32_e64 v111, 0, v111, s[98:99]
	v_cndmask_b32_e64 v177, 0, v177, s[98:99]
	v_mov_b32_e32 v113, 0
	v_mov_b32_e32 v176, v110
	v_mov_b32_e32 v178, 0
	v_mov_b32_e32 v179, 0
	s_mov_b32 s99, 0
	s_min_i32 s3, s100, s101
	s_mul_i32 s98, s3, 0x218000
	s_add_i32 s32, s53, s73
	s_mov_b32 m0, s32
	v_lshl_add_u64 v[106:107], v[102:103], 0, s[98:99]
	v_lshl_add_u64 v[108:109], v[104:105], 0, s[98:99]
	global_load_lds_dwordx4 v[106:107], off
	s_add_i32 m0, s32, 0x380
	s_lshr_b32 s3, s73, 1
	s_add_i32 s3, s3, s53
	global_load_lds_dwordx4 v[106:107], off offset:128
	s_add_i32 m0, s3, 0x10000
	s_add_i32 s100, s100, 1
	s_add_i32 s53, s53, 0x4000
	global_load_lds_dwordx4 v[108:109], off
	s_and_b32 s53, s53, 0xc000
	s_min_i32 s3, s100, s101
	s_mul_i32 s98, s3, 0x218000
	s_add_i32 s32, s53, s73
	s_mov_b32 m0, s32
	v_lshl_add_u64 v[106:107], v[102:103], 0, s[98:99]
	v_lshl_add_u64 v[108:109], v[104:105], 0, s[98:99]
	global_load_lds_dwordx4 v[106:107], off
	s_add_i32 m0, s32, 0x380
	s_lshr_b32 s3, s73, 1
	s_add_i32 s3, s3, s53
	global_load_lds_dwordx4 v[106:107], off offset:128
	s_add_i32 m0, s3, 0x10000
	s_add_i32 s100, s100, 1
	s_add_i32 s53, s53, 0x4000
	global_load_lds_dwordx4 v[108:109], off
	s_and_b32 s53, s53, 0xc000
	s_min_i32 s3, s100, s101
	s_mul_i32 s98, s3, 0x218000
	s_add_i32 s32, s53, s73
	s_mov_b32 m0, s32
	v_lshl_add_u64 v[106:107], v[102:103], 0, s[98:99]
	v_lshl_add_u64 v[108:109], v[104:105], 0, s[98:99]
	global_load_lds_dwordx4 v[106:107], off
	s_add_i32 m0, s32, 0x380
	s_lshr_b32 s3, s73, 1
	s_add_i32 s3, s3, s53
	global_load_lds_dwordx4 v[106:107], off offset:128
	s_add_i32 m0, s3, 0x10000
	s_add_i32 s100, s100, 1
	s_add_i32 s53, s53, 0x4000
	global_load_lds_dwordx4 v[108:109], off
	s_and_b32 s53, s53, 0xc000

; #define MFMA32(a, b, c) __builtin_amdgcn_mfma_f32_32x32x16_bf16((a), (b), (c), 0, 0, 0)
; #define SBAR() __builtin_amdgcn_sched_barrier(0)
; template <int D0> __device__ __forceinline__ void pv_one(f32x16& od, int vb, bf16x8 pa0, bf16x8 pa1, bf16x8 pa2, bf16x8 pa3) {
;     const s16x4 l0 = tr_read<v_rd_off(D0, 0, 0)>(vb), h0 = tr_read<v_rd_off(D0, 0, 1)>(vb), l1 = tr_read<v_rd_off(D0, 1, 0)>(vb), h1 = tr_read<v_rd_off(D0, 1, 1)>(vb);
;     const s16x4 l2 = tr_read<v_rd_off(D0, 2, 0)>(vb), h2 = tr_read<v_rd_off(D0, 2, 1)>(vb), l3 = tr_read<v_rd_off(D0, 3, 0)>(vb), h3 = tr_read<v_rd_off(D0, 3, 1)>(vb);
;     asm volatile("s_waitcnt lgkmcnt(0)" ::: "memory"); SBAR();
;     ...
;     od = MFMA32(pa0, PK(l0, h0), od); od = MFMA32(pa1, PK(l1, h1), od); od = MFMA32(pa2, PK(l2, h2), od); od = MFMA32(pa3, PK(l3, h3), od);
;     ...
; }
; __device__ __forceinline__ void pv_d0(f32x16* o, int vb, bf16x8 pa0, bf16x8 pa1, bf16x8 pa2, bf16x8 pa3) {
;     pv_one<0>(o[0], vb, pa0, pa1, pa2, pa3); pv_one<1>(o[1], vb, pa0, pa1, pa2, pa3); pv_one<2>(o[2], vb, pa0, pa1, pa2, pa3); pv_one<3>(o[3], vb, pa0, pa1, pa2, pa3);
; template <bool FIXED>
; __device__ __forceinline__ float softmax_tile(f32x16& p0, f32x16& p1, float& m_reg, float& l_reg, bf16x8& pa0, bf16x8& pa1, bf16x8& pa2, bf16x8& pa3) {
;     ...
; #pragma unroll
;         for (int r = 0; r < 16; ++r) { p0[r] = __builtin_amdgcn_exp2f(p0[r]); p1[r] = __builtin_amdgcn_exp2f(p1[r]); }
;     }
;     float ps = 0.f;
; #pragma unroll
;     for (int r = 0; r < 16; ++r) ps += p0[r];
; #pragma unroll
;     for (int r = 0; r < 16; ++r) ps += p1[r];
;     ps = half_sum(ps);
;     l_reg = l_reg * alpha + ps;
;     ...
;     PK4(p0, 0, pa0); PK4(p0, 8, pa1); PK4(p1, 0, pa2); PK4(p1, 8, pa3);
.Lattn_exp2:
	v_add_u32_e32 v5, s29, v200
	ds_read_b64_tr_b16 v[228:229], v5 offset:0
	ds_read_b64_tr_b16 v[230:231], v5 offset:2048
	ds_read_b64_tr_b16 v[240:241], v5 offset:512
	ds_read_b64_tr_b16 v[242:243], v5 offset:2560
	ds_read_b64_tr_b16 v[244:245], v5 offset:1024
	ds_read_b64_tr_b16 v[246:247], v5 offset:3072
	s_nop 2
	v_exp_f32_e32 v70, v70
	v_exp_f32_e32 v71, v71
	v_add_f32_e32 v2, 0, v70
	v_exp_f32_e32 v72, v72
	v_add_f32_e32 v2, v71, v2
	v_exp_f32_e32 v73, v73
	v_add_f32_e32 v2, v72, v2
	v_exp_f32_e32 v74, v74
	v_add_f32_e32 v2, v73, v2
	v_exp_f32_e32 v75, v75
	v_add_f32_e32 v2, v74, v2
	v_exp_f32_e32 v76, v76
	v_add_f32_e32 v2, v75, v2
	v_exp_f32_e32 v77, v77
	v_add_f32_e32 v2, v76, v2
	v_cvt_pk_bf16_f32 v70, v70, v71
	v_add_f32_e32 v2, v77, v2
	v_cvt_pk_bf16_f32 v71, v72, v73
	v_cvt_pk_bf16_f32 v72, v74, v75
	v_cvt_pk_bf16_f32 v73, v76, v77
	ds_read_b64_tr_b16 v[74:75], v5 offset:1536
	ds_read_b64_tr_b16 v[76:77], v5 offset:3584
	v_permlane32_swap_b32_e32 v70, v72
	v_permlane32_swap_b32_e32 v71, v73
	s_waitcnt lgkmcnt(6)
	s_nop 0
	v_mfma_f32_32x32x16_bf16 v[54:69], v[70:73], v[228:231], v[54:69]
	ds_read_b64_tr_b16 v[228:229], v5 offset:4096
	ds_read_b64_tr_b16 v[230:231], v5 offset:6144
	v_exp_f32_e32 v78, v78
	v_exp_f32_e32 v79, v79
	v_add_f32_e32 v2, v78, v2
	v_exp_f32_e32 v80, v80
	v_add_f32_e32 v2, v79, v2
	v_exp_f32_e32 v81, v81
	s_waitcnt lgkmcnt(6)
	v_mfma_f32_32x32x16_bf16 v[38:53], v[70:73], v[240:243], v[38:53]
	ds_read_b64_tr_b16 v[240:241], v5 offset:4608
	ds_read_b64_tr_b16 v[242:243], v5 offset:6656
	v_add_f32_e32 v2, v80, v2
	v_exp_f32_e32 v82, v82
	v_add_f32_e32 v2, v81, v2
	v_exp_f32_e32 v83, v83
	v_add_f32_e32 v2, v82, v2
	v_exp_f32_e32 v84, v84
	s_waitcnt lgkmcnt(6)
	v_mfma_f32_32x32x16_bf16 v[22:37], v[70:73], v[244:247], v[22:37]
	ds_read_b64_tr_b16 v[244:245], v5 offset:5120
	ds_read_b64_tr_b16 v[246:247], v5 offset:7168
	v_add_f32_e32 v2, v83, v2
	v_exp_f32_e32 v85, v85
	v_add_f32_e32 v2, v84, v2
	v_cvt_pk_bf16_f32 v78, v78, v79
	v_add_f32_e32 v2, v85, v2
	s_waitcnt lgkmcnt(6)
	v_mfma_f32_32x32x16_bf16 v[6:21], v[70:73], v[74:77], v[6:21]
	v_cvt_pk_bf16_f32 v79, v80, v81
	v_cvt_pk_bf16_f32 v80, v82, v83
	v_cvt_pk_bf16_f32 v81, v84, v85
	ds_read_b64_tr_b16 v[74:75], v5 offset:5632
	ds_read_b64_tr_b16 v[76:77], v5 offset:7680
	v_permlane32_swap_b32_e32 v78, v80
	v_permlane32_swap_b32_e32 v79, v81
	s_waitcnt lgkmcnt(6)
	s_nop 0
	v_mfma_f32_32x32x16_bf16 v[54:69], v[78:81], v[228:231], v[54:69]
	ds_read_b64_tr_b16 v[228:229], v5 offset:8192
	ds_read_b64_tr_b16 v[230:231], v5 offset:10240
	v_exp_f32_e32 v86, v86
	v_exp_f32_e32 v87, v87
	v_add_f32_e32 v2, v86, v2
	v_exp_f32_e32 v88, v88
	v_add_f32_e32 v2, v87, v2
	v_exp_f32_e32 v89, v89
	s_waitcnt lgkmcnt(6)
	v_mfma_f32_32x32x16_bf16 v[38:53], v[78:81], v[240:243], v[38:53]
	ds_read_b64_tr_b16 v[240:241], v5 offset:8704
	ds_read_b64_tr_b16 v[242:243], v5 offset:10752
	v_add_f32_e32 v2, v88, v2
	v_exp_f32_e32 v90, v90
	v_add_f32_e32 v2, v89, v2
	v_exp_f32_e32 v91, v91
	v_add_f32_e32 v2, v90, v2
	v_exp_f32_e32 v92, v92
	s_waitcnt lgkmcnt(6)
	v_mfma_f32_32x32x16_bf16 v[22:37], v[78:81], v[244:247], v[22:37]
	ds_read_b64_tr_b16 v[244:245], v5 offset:9216
	ds_read_b64_tr_b16 v[246:247], v5 offset:11264
	v_add_f32_e32 v2, v91, v2
	v_exp_f32_e32 v93, v93
	v_add_f32_e32 v2, v92, v2
	v_cvt_pk_bf16_f32 v86, v86, v87
	v_add_f32_e32 v2, v93, v2
	s_waitcnt lgkmcnt(6)
	v_mfma_f32_32x32x16_bf16 v[6:21], v[78:81], v[74:77], v[6:21]
	v_cvt_pk_bf16_f32 v87, v88, v89
	v_cvt_pk_bf16_f32 v88, v90, v91
	v_cvt_pk_bf16_f32 v89, v92, v93
	ds_read_b64_tr_b16 v[74:75], v5 offset:9728
	ds_read_b64_tr_b16 v[76:77], v5 offset:11776
	v_permlane32_swap_b32_e32 v86, v88
	v_permlane32_swap_b32_e32 v87, v89
	s_waitcnt lgkmcnt(6)
	s_nop 0
	v_mfma_f32_32x32x16_bf16 v[54:69], v[86:89], v[228:231], v[54:69]
	ds_read_b64_tr_b16 v[228:229], v5 offset:12288
	ds_read_b64_tr_b16 v[230:231], v5 offset:14336
	v_exp_f32_e32 v94, v94
	v_exp_f32_e32 v95, v95
	v_add_f32_e32 v2, v94, v2
	v_exp_f32_e32 v96, v96
	v_add_f32_e32 v2, v95, v2
	v_exp_f32_e32 v97, v97
	s_waitcnt lgkmcnt(6)
	v_mfma_f32_32x32x16_bf16 v[38:53], v[86:89], v[240:243], v[38:53]
	ds_read_b64_tr_b16 v[240:241], v5 offset:12800
	ds_read_b64_tr_b16 v[242:243], v5 offset:14848
	v_add_f32_e32 v2, v96, v2
	v_exp_f32_e32 v98, v98
	v_add_f32_e32 v2, v97, v2
	v_exp_f32_e32 v99, v99
	v_add_f32_e32 v2, v98, v2
	v_exp_f32_e32 v100, v100
	s_waitcnt lgkmcnt(6)
	v_mfma_f32_32x32x16_bf16 v[22:37], v[86:89], v[244:247], v[22:37]
	ds_read_b64_tr_b16 v[244:245], v5 offset:13312
	ds_read_b64_tr_b16 v[246:247], v5 offset:15360
	v_add_f32_e32 v2, v99, v2
	v_exp_f32_e32 v101, v101
	v_add_f32_e32 v2, v100, v2
	v_cvt_pk_bf16_f32 v94, v94, v95
	v_add_f32_e32 v2, v101, v2
	s_waitcnt lgkmcnt(6)
	v_mfma_f32_32x32x16_bf16 v[6:21], v[86:89], v[74:77], v[6:21]
	v_cvt_pk_bf16_f32 v95, v96, v97
	v_cvt_pk_bf16_f32 v96, v98, v99
	v_cvt_pk_bf16_f32 v97, v100, v101
	ds_read_b64_tr_b16 v[74:75], v5 offset:13824
	ds_read_b64_tr_b16 v[76:77], v5 offset:15872
	v_permlane32_swap_b32_e32 v94, v96
	v_permlane32_swap_b32_e32 v95, v97
	v_mov_b32_e32 v3, v2
	s_waitcnt lgkmcnt(6)
	s_nop 0
	v_mfma_f32_32x32x16_bf16 v[54:69], v[94:97], v[228:231], v[54:69]
	v_mov_b32_e32 v236, v238
	s_waitcnt lgkmcnt(4)
	v_mfma_f32_32x32x16_bf16 v[38:53], v[94:97], v[240:243], v[38:53]
	v_permlane32_swap_b32_e32 v2, v3
	s_waitcnt lgkmcnt(2)
	v_mfma_f32_32x32x16_bf16 v[22:37], v[94:97], v[244:247], v[22:37]
	s_waitcnt lgkmcnt(0)
	v_mfma_f32_32x32x16_bf16 v[6:21], v[94:97], v[74:77], v[6:21]
	v_add_f32_e32 v2, v2, v3
	v_add_f32_e32 v219, v219, v2

.LBB0_937:
	s_add_i32 s10, s60, 0xffffc000
	s_and_b32 s29, s10, 0xc000
	s_add_i32 s14, s29, 0x8000
	v_add_u32_e32 v2, 1, v236
	v_cmp_ge_i32_e32 vcc, v2, v188
	v_add_u32_e32 v237, 64, v235
	v_add_u32_e32 v2, s14, v207
	s_waitcnt vmcnt(6)
	s_waitcnt lgkmcnt(0)
	s_barrier
	v_add_u32_e32 v3, v2, v167
	ds_read_b128 v[70:73], v3 offset:32768
	v_add_u32_e32 v3, v2, v212
	ds_read_b128 v[90:93], v3 offset:32768
	v_add_u32_e32 v3, v2, v214
	ds_read_b128 v[94:97], v3 offset:32768
	v_add_u32_e32 v3, v2, v216
	ds_read_b128 v[98:101], v3 offset:32768
	v_add_u32_e32 v3, s14, v211
	ds_read_b128 v[86:89], v3 offset:32768
	v_add_u32_e32 v3, s14, v213
	ds_read_b128 v[228:231], v3 offset:32768
	v_add_u32_e32 v3, s14, v215
	ds_read_b128 v[240:243], v3 offset:32768
	v_add_u32_e32 v3, s14, v217
	ds_read_b128 v[244:247], v3 offset:32768
	v_add_u32_e32 v3, 63, v235
	v_cmp_le_i32_e64 s[12:13], s27, v3
	v_cmp_gt_i32_e64 s[10:11], s27, v3
	v_cmp_ge_i32_e64 s[14:15], s18, v235
	v_cvt_f32_i32_e32 v2, v235
	s_and_b64 s[12:13], s[12:13], s[14:15]
	s_min_i32 s3, s100, s101
	s_mul_i32 s98, s3, 0x218000
	s_add_i32 s32, s53, s73
	s_mov_b32 m0, s32
	v_lshl_add_u64 v[106:107], v[102:103], 0, s[98:99]
	v_lshl_add_u64 v[108:109], v[104:105], 0, s[98:99]
	global_load_lds_dwordx4 v[106:107], off
	s_add_i32 m0, s32, 0x380
	s_lshr_b32 s3, s73, 1
	s_add_i32 s3, s3, s53
	global_load_lds_dwordx4 v[106:107], off offset:128
	s_add_i32 m0, s3, 0x10000
	s_add_i32 s100, s100, 1
	s_add_i32 s53, s53, 0x4000
	global_load_lds_dwordx4 v[108:109], off
	s_and_b32 s53, s53, 0xc000
	s_cmp_eq_u64 s[12:13], 0
	s_cbranch_scc0 .Lattn_nl1
	s_waitcnt lgkmcnt(7)
	v_mfma_f32_32x32x16_bf16 v[70:85], v[70:73], v[114:117], 0
	v_cndmask_b32_e64 v3, -v189, v189, s[10:11]
	v_sub_f32_e32 v2, v191, v2
	v_mul_f32_e64 v2, v2, -v3
	v_cvt_pk_bf16_f32 v5, v2, v3
	v_lshlrev_b32_e32 v196, 16, v5
	v_and_b32_e32 v197, 0xffff0000, v5
	s_waitcnt lgkmcnt(6)
	v_mfma_f32_32x32x16_bf16 v[70:85], v[90:93], v[118:121], v[70:85]
	v_pk_add_f32 v[2:3], v[2:3], v[196:197] neg_lo:[0,1] neg_hi:[0,1]
	s_nop 0
	v_cvt_pk_bf16_f32 v2, v2, v3
	v_and_b32_e32 v3, 0xffff, v5
	v_lshl_or_b32 v183, v2, 16, v3
	s_waitcnt lgkmcnt(5)
	v_mfma_f32_32x32x16_bf16 v[70:85], v[94:97], v[122:125], v[70:85]
	v_lshrrev_b32_e32 v3, 16, v5
	v_and_or_b32 v2, v2, s28, v3
	v_cndmask_b32_e64 v3, 0, v2, s[4:5]
	v_cndmask_b32_e64 v2, 0, v183, s[4:5]
	v_mov_b32_e32 v5, v4
	s_waitcnt lgkmcnt(4)
	v_mfma_f32_32x32x16_bf16 v[70:85], v[98:101], v[126:129], v[70:85]
	s_waitcnt lgkmcnt(3)
	v_mfma_f32_32x32x16_bf16 v[86:101], v[86:89], v[114:117], 0
	s_waitcnt lgkmcnt(2)
	v_mfma_f32_32x32x16_bf16 v[86:101], v[228:231], v[118:121], v[86:101]
	s_waitcnt lgkmcnt(1)
	v_mfma_f32_32x32x16_bf16 v[86:101], v[240:243], v[122:125], v[86:101]
	s_waitcnt lgkmcnt(0)
	v_mfma_f32_32x32x16_bf16 v[86:101], v[244:247], v[126:129], v[86:101]
	v_mfma_f32_32x32x16_bf16 v[70:85], v[110:113], v[2:5], v[70:85]
	v_mfma_f32_32x32x16_bf16 v[86:101], v[176:179], v[2:5], v[86:101]
	s_branch .Lattn_exp1
.Lattn_nl1:
	s_waitcnt lgkmcnt(7)
	v_mfma_f32_32x32x16_bf16 v[70:85], v[70:73], v[114:117], 0
	s_waitcnt lgkmcnt(6)
	v_mfma_f32_32x32x16_bf16 v[70:85], v[90:93], v[118:121], v[70:85]
	s_waitcnt lgkmcnt(5)
	v_mfma_f32_32x32x16_bf16 v[70:85], v[94:97], v[122:125], v[70:85]
	s_waitcnt lgkmcnt(4)
	v_mfma_f32_32x32x16_bf16 v[70:85], v[98:101], v[126:129], v[70:85]
	s_waitcnt lgkmcnt(3)
	v_mfma_f32_32x32x16_bf16 v[86:101], v[86:89], v[114:117], 0
	s_waitcnt lgkmcnt(2)
	v_mfma_f32_32x32x16_bf16 v[86:101], v[228:231], v[118:121], v[86:101]
	s_waitcnt lgkmcnt(1)
	v_mfma_f32_32x32x16_bf16 v[86:101], v[240:243], v[122:125], v[86:101]
	s_waitcnt lgkmcnt(0)
	v_mfma_f32_32x32x16_bf16 v[86:101], v[244:247], v[126:129], v[86:101]
	s_and_saveexec_b64 s[14:15], s[12:13]
	s_xor_b64 s[12:13], exec, s[14:15]
	s_cbranch_execz .LBB0_941
	v_sub_f32_e32 v2, v190, v2
	s_mov_b32 s14, -2.0
	v_add_f32_e32 v3, -1.0, v2
	s_mov_b32 s15, 0xc0400000
	v_pk_add_f32 v[196:197], v[2:3], s[14:15] op_sel_hi:[0,1]
	v_pk_add_f32 v[228:229], v[2:3], s[62:63] op_sel_hi:[0,1]
	v_pk_add_f32 v[230:231], v[2:3], s[74:75] op_sel_hi:[0,1]
	v_pk_add_f32 v[238:239], v[2:3], s[82:83] op_sel_hi:[0,1]
	v_pk_add_f32 v[240:241], v[2:3], s[94:95] op_sel_hi:[0,1]
	v_pk_add_f32 v[242:243], v[2:3], s[24:25] op_sel_hi:[0,1]
	v_pk_add_f32 v[244:245], v[2:3], s[56:57] op_sel_hi:[0,1]
	s_mov_b32 s14, 0xc2000000
	v_and_b32_e32 v197, 0x7fffffff, v197
	v_and_b32_e32 v196, 0x7fffffff, v196
	v_and_b32_e32 v229, 0x7fffffff, v229
	v_and_b32_e32 v228, 0x7fffffff, v228
	v_and_b32_e32 v231, 0x7fffffff, v231
	v_and_b32_e32 v230, 0x7fffffff, v230
	v_and_b32_e32 v239, 0x7fffffff, v239
	v_and_b32_e32 v238, 0x7fffffff, v238
	v_and_b32_e32 v241, 0x7fffffff, v241
	v_and_b32_e32 v240, 0x7fffffff, v240
	v_and_b32_e32 v243, 0x7fffffff, v243
	v_and_b32_e32 v242, 0x7fffffff, v242
	v_and_b32_e32 v245, 0x7fffffff, v245
	v_and_b32_e32 v244, 0x7fffffff, v244
	v_mov_b32_e32 v183, v182
	s_mov_b32 s15, 0xc2040000
	v_and_b32_e32 v246, 0x7fffffff, v2
	v_and_b32_e32 v247, 0x7fffffff, v3
	v_pk_fma_f32 v[84:85], v[182:183], v[244:245], v[84:85]
	v_pk_fma_f32 v[82:83], v[182:183], v[242:243], v[82:83]
	v_pk_fma_f32 v[80:81], v[182:183], v[240:241], v[80:81]
	v_pk_fma_f32 v[78:79], v[182:183], v[238:239], v[78:79]
	v_pk_fma_f32 v[76:77], v[182:183], v[230:231], v[76:77]
	v_pk_fma_f32 v[74:75], v[182:183], v[228:229], v[74:75]
	v_pk_fma_f32 v[72:73], v[182:183], v[196:197], v[72:73]
	v_pk_add_f32 v[196:197], v[2:3], s[58:59] op_sel_hi:[0,1]
	v_pk_add_f32 v[228:229], v[2:3], s[0:1] op_sel_hi:[0,1]
	v_pk_add_f32 v[230:231], v[2:3], s[20:21] op_sel_hi:[0,1]
	v_pk_add_f32 v[238:239], v[2:3], s[86:87] op_sel_hi:[0,1]
	v_pk_add_f32 v[240:241], v[2:3], s[78:79] op_sel_hi:[0,1]
	v_pk_add_f32 v[242:243], v[2:3], s[66:67] op_sel_hi:[0,1]
	v_pk_add_f32 v[244:245], v[2:3], s[54:55] op_sel_hi:[0,1]
	v_pk_add_f32 v[2:3], v[2:3], s[14:15] op_sel_hi:[0,1]
	v_and_b32_e32 v3, 0x7fffffff, v3
	v_and_b32_e32 v2, 0x7fffffff, v2
	v_and_b32_e32 v245, 0x7fffffff, v245
	v_and_b32_e32 v244, 0x7fffffff, v244
	v_and_b32_e32 v243, 0x7fffffff, v243
	v_and_b32_e32 v242, 0x7fffffff, v242
	v_and_b32_e32 v241, 0x7fffffff, v241
	v_and_b32_e32 v240, 0x7fffffff, v240
	v_and_b32_e32 v239, 0x7fffffff, v239
	v_and_b32_e32 v238, 0x7fffffff, v238
	v_and_b32_e32 v231, 0x7fffffff, v231
	v_and_b32_e32 v230, 0x7fffffff, v230
	v_and_b32_e32 v229, 0x7fffffff, v229
	v_and_b32_e32 v228, 0x7fffffff, v228
	v_and_b32_e32 v197, 0x7fffffff, v197
	v_and_b32_e32 v196, 0x7fffffff, v196
	v_pk_fma_f32 v[70:71], v[184:185], v[246:247], v[70:71]
	v_pk_fma_f32 v[100:101], v[182:183], v[196:197], v[100:101]
	v_pk_fma_f32 v[98:99], v[182:183], v[228:229], v[98:99]
	v_pk_fma_f32 v[96:97], v[182:183], v[230:231], v[96:97]
	v_pk_fma_f32 v[94:95], v[182:183], v[238:239], v[94:95]
	v_pk_fma_f32 v[92:93], v[182:183], v[240:241], v[92:93]
	v_pk_fma_f32 v[90:91], v[182:183], v[242:243], v[90:91]
	v_pk_fma_f32 v[88:89], v[182:183], v[244:245], v[88:89]
	v_pk_fma_f32 v[86:87], v[184:185], v[2:3], v[86:87]

; #define MFMA32(a, b, c) __builtin_amdgcn_mfma_f32_32x32x16_bf16((a), (b), (c), 0, 0, 0)
; #define SBAR() __builtin_amdgcn_sched_barrier(0)
; template <int D0> __device__ __forceinline__ void pv_one(f32x16& od, int vb, bf16x8 pa0, bf16x8 pa1, bf16x8 pa2, bf16x8 pa3) {
;     const s16x4 l0 = tr_read<v_rd_off(D0, 0, 0)>(vb), h0 = tr_read<v_rd_off(D0, 0, 1)>(vb), l1 = tr_read<v_rd_off(D0, 1, 0)>(vb), h1 = tr_read<v_rd_off(D0, 1, 1)>(vb);
;     const s16x4 l2 = tr_read<v_rd_off(D0, 2, 0)>(vb), h2 = tr_read<v_rd_off(D0, 2, 1)>(vb), l3 = tr_read<v_rd_off(D0, 3, 0)>(vb), h3 = tr_read<v_rd_off(D0, 3, 1)>(vb);
;     asm volatile("s_waitcnt lgkmcnt(0)" ::: "memory"); SBAR();
;     ...
;     od = MFMA32(pa0, PK(l0, h0), od); od = MFMA32(pa1, PK(l1, h1), od); od = MFMA32(pa2, PK(l2, h2), od); od = MFMA32(pa3, PK(l3, h3), od);
;     ...
; }
; __device__ __forceinline__ void pv_d0(f32x16* o, int vb, bf16x8 pa0, bf16x8 pa1, bf16x8 pa2, bf16x8 pa3) {
;     pv_one<0>(o[0], vb, pa0, pa1, pa2, pa3); pv_one<1>(o[1], vb, pa0, pa1, pa2, pa3); pv_one<2>(o[2], vb, pa0, pa1, pa2, pa3); pv_one<3>(o[3], vb, pa0, pa1, pa2, pa3);
; template <bool FIXED>
; __device__ __forceinline__ float softmax_tile(f32x16& p0, f32x16& p1, float& m_reg, float& l_reg, bf16x8& pa0, bf16x8& pa1, bf16x8& pa2, bf16x8& pa3) {
;     ...
; #pragma unroll
;         for (int r = 0; r < 16; ++r) { p0[r] = __builtin_amdgcn_exp2f(p0[r]); p1[r] = __builtin_amdgcn_exp2f(p1[r]); }
;     }
;     float ps = 0.f;
; #pragma unroll
;     for (int r = 0; r < 16; ++r) ps += p0[r];
; #pragma unroll
;     for (int r = 0; r < 16; ++r) ps += p1[r];
;     ps = half_sum(ps);
;     l_reg = l_reg * alpha + ps;
;     ...
;     PK4(p0, 0, pa0); PK4(p0, 8, pa1); PK4(p1, 0, pa2); PK4(p1, 8, pa3);
; template <int MODE, bool FIXED>
; __device__ __forceinline__ void attn_unit(LAS unsigned char* lds, unsigned char* ws, const AttnParams& P, int l, int Tp, int sq, int h, int qb, int part, int np, int pslot, int tid, int wave, int lane) {
;     ...
;         for (int j = jlo; j < jhi; j += 2) {
;             TILE(sA, j);
;             if (j + 1 < jhi) { if (DEPTH == 2) TILE(sB, j + 1); else TILE(sA, j + 1); }
.Lattn_exp1:
	v_add_u32_e32 v5, s29, v200
	ds_read_b64_tr_b16 v[228:229], v5 offset:0
	ds_read_b64_tr_b16 v[230:231], v5 offset:2048
	ds_read_b64_tr_b16 v[240:241], v5 offset:512
	ds_read_b64_tr_b16 v[242:243], v5 offset:2560
	ds_read_b64_tr_b16 v[244:245], v5 offset:1024
	ds_read_b64_tr_b16 v[246:247], v5 offset:3072
	s_nop 2
	v_exp_f32_e32 v70, v70
	v_exp_f32_e32 v71, v71
	v_add_f32_e32 v2, 0, v70
	v_exp_f32_e32 v72, v72
	v_add_f32_e32 v2, v71, v2
	v_exp_f32_e32 v73, v73
	v_add_f32_e32 v2, v72, v2
	v_exp_f32_e32 v74, v74
	v_add_f32_e32 v2, v73, v2
	v_exp_f32_e32 v75, v75
	v_add_f32_e32 v2, v74, v2
	v_exp_f32_e32 v76, v76
	v_add_f32_e32 v2, v75, v2
	v_exp_f32_e32 v77, v77
	v_add_f32_e32 v2, v76, v2
	v_cvt_pk_bf16_f32 v70, v70, v71
	v_add_f32_e32 v2, v77, v2
	v_cvt_pk_bf16_f32 v71, v72, v73
	v_cvt_pk_bf16_f32 v72, v74, v75
	v_cvt_pk_bf16_f32 v73, v76, v77
	ds_read_b64_tr_b16 v[74:75], v5 offset:1536
	ds_read_b64_tr_b16 v[76:77], v5 offset:3584
	v_permlane32_swap_b32_e32 v70, v72
	v_permlane32_swap_b32_e32 v71, v73
	s_waitcnt lgkmcnt(6)
	s_nop 0
	v_mfma_f32_32x32x16_bf16 v[54:69], v[70:73], v[228:231], v[54:69]
	ds_read_b64_tr_b16 v[228:229], v5 offset:4096
	ds_read_b64_tr_b16 v[230:231], v5 offset:6144
	v_exp_f32_e32 v78, v78
	v_exp_f32_e32 v79, v79
	v_add_f32_e32 v2, v78, v2
	v_exp_f32_e32 v80, v80
	v_add_f32_e32 v2, v79, v2
	v_exp_f32_e32 v81, v81
	s_waitcnt lgkmcnt(6)
	v_mfma_f32_32x32x16_bf16 v[38:53], v[70:73], v[240:243], v[38:53]
	ds_read_b64_tr_b16 v[240:241], v5 offset:4608
	ds_read_b64_tr_b16 v[242:243], v5 offset:6656
	v_add_f32_e32 v2, v80, v2
	v_exp_f32_e32 v82, v82
	v_add_f32_e32 v2, v81, v2
	v_exp_f32_e32 v83, v83
	v_add_f32_e32 v2, v82, v2
	v_exp_f32_e32 v84, v84
	s_waitcnt lgkmcnt(6)
	v_mfma_f32_32x32x16_bf16 v[22:37], v[70:73], v[244:247], v[22:37]
	ds_read_b64_tr_b16 v[244:245], v5 offset:5120
	ds_read_b64_tr_b16 v[246:247], v5 offset:7168
	v_add_f32_e32 v2, v83, v2
	v_exp_f32_e32 v85, v85
	v_add_f32_e32 v2, v84, v2
	v_cvt_pk_bf16_f32 v78, v78, v79
	v_add_f32_e32 v2, v85, v2
	s_waitcnt lgkmcnt(6)
	v_mfma_f32_32x32x16_bf16 v[6:21], v[70:73], v[74:77], v[6:21]
	v_cvt_pk_bf16_f32 v79, v80, v81
	v_cvt_pk_bf16_f32 v80, v82, v83
	v_cvt_pk_bf16_f32 v81, v84, v85
	ds_read_b64_tr_b16 v[74:75], v5 offset:5632
	ds_read_b64_tr_b16 v[76:77], v5 offset:7680
	v_permlane32_swap_b32_e32 v78, v80
	v_permlane32_swap_b32_e32 v79, v81
	s_waitcnt lgkmcnt(6)
	s_nop 0
	v_mfma_f32_32x32x16_bf16 v[54:69], v[78:81], v[228:231], v[54:69]
	ds_read_b64_tr_b16 v[228:229], v5 offset:8192
	ds_read_b64_tr_b16 v[230:231], v5 offset:10240
	v_exp_f32_e32 v86, v86
	v_exp_f32_e32 v87, v87
	v_add_f32_e32 v2, v86, v2
	v_exp_f32_e32 v88, v88
	v_add_f32_e32 v2, v87, v2
	v_exp_f32_e32 v89, v89
	s_waitcnt lgkmcnt(6)
	v_mfma_f32_32x32x16_bf16 v[38:53], v[78:81], v[240:243], v[38:53]
	ds_read_b64_tr_b16 v[240:241], v5 offset:8704
	ds_read_b64_tr_b16 v[242:243], v5 offset:10752
	v_add_f32_e32 v2, v88, v2
	v_exp_f32_e32 v90, v90
	v_add_f32_e32 v2, v89, v2
	v_exp_f32_e32 v91, v91
	v_add_f32_e32 v2, v90, v2
	v_exp_f32_e32 v92, v92
	s_waitcnt lgkmcnt(6)
	v_mfma_f32_32x32x16_bf16 v[22:37], v[78:81], v[244:247], v[22:37]
	ds_read_b64_tr_b16 v[244:245], v5 offset:9216
	ds_read_b64_tr_b16 v[246:247], v5 offset:11264
	v_add_f32_e32 v2, v91, v2
	v_exp_f32_e32 v93, v93
	v_add_f32_e32 v2, v92, v2
	v_cvt_pk_bf16_f32 v86, v86, v87
	v_add_f32_e32 v2, v93, v2
	s_waitcnt lgkmcnt(6)
	v_mfma_f32_32x32x16_bf16 v[6:21], v[78:81], v[74:77], v[6:21]
	v_cvt_pk_bf16_f32 v87, v88, v89
	v_cvt_pk_bf16_f32 v88, v90, v91
	v_cvt_pk_bf16_f32 v89, v92, v93
	ds_read_b64_tr_b16 v[74:75], v5 offset:9728
	ds_read_b64_tr_b16 v[76:77], v5 offset:11776
	v_permlane32_swap_b32_e32 v86, v88
	v_permlane32_swap_b32_e32 v87, v89
	s_waitcnt lgkmcnt(6)
	s_nop 0
	v_mfma_f32_32x32x16_bf16 v[54:69], v[86:89], v[228:231], v[54:69]
	ds_read_b64_tr_b16 v[228:229], v5 offset:12288
	ds_read_b64_tr_b16 v[230:231], v5 offset:14336
	v_exp_f32_e32 v94, v94
	v_exp_f32_e32 v95, v95
	v_add_f32_e32 v2, v94, v2
	v_exp_f32_e32 v96, v96
	v_add_f32_e32 v2, v95, v2
	v_exp_f32_e32 v97, v97
	s_waitcnt lgkmcnt(6)
	v_mfma_f32_32x32x16_bf16 v[38:53], v[86:89], v[240:243], v[38:53]
	ds_read_b64_tr_b16 v[240:241], v5 offset:12800
	ds_read_b64_tr_b16 v[242:243], v5 offset:14848
	v_add_f32_e32 v2, v96, v2
	v_exp_f32_e32 v98, v98
	v_add_f32_e32 v2, v97, v2
	v_exp_f32_e32 v99, v99
	v_add_f32_e32 v2, v98, v2
	v_exp_f32_e32 v100, v100
	s_waitcnt lgkmcnt(6)
	v_mfma_f32_32x32x16_bf16 v[22:37], v[86:89], v[244:247], v[22:37]
	ds_read_b64_tr_b16 v[244:245], v5 offset:13312
	ds_read_b64_tr_b16 v[246:247], v5 offset:15360
	v_add_f32_e32 v2, v99, v2
	v_exp_f32_e32 v101, v101
	v_add_f32_e32 v2, v100, v2
	v_cvt_pk_bf16_f32 v94, v94, v95
	v_add_f32_e32 v2, v101, v2
	s_waitcnt lgkmcnt(6)
	v_mfma_f32_32x32x16_bf16 v[6:21], v[86:89], v[74:77], v[6:21]
	v_cvt_pk_bf16_f32 v95, v96, v97
	v_cvt_pk_bf16_f32 v96, v98, v99
	v_cvt_pk_bf16_f32 v97, v100, v101
	ds_read_b64_tr_b16 v[74:75], v5 offset:13824
	ds_read_b64_tr_b16 v[76:77], v5 offset:15872
	v_permlane32_swap_b32_e32 v94, v96
	v_permlane32_swap_b32_e32 v95, v97
	v_mov_b32_e32 v3, v2
	s_waitcnt lgkmcnt(6)
	s_nop 0
	v_mfma_f32_32x32x16_bf16 v[54:69], v[94:97], v[228:231], v[54:69]
	v_add_u32_e32 v238, 2, v236
	s_waitcnt lgkmcnt(4)
	v_mfma_f32_32x32x16_bf16 v[38:53], v[94:97], v[240:243], v[38:53]
	v_permlane32_swap_b32_e32 v2, v3
	s_waitcnt lgkmcnt(2)
	v_mfma_f32_32x32x16_bf16 v[22:37], v[94:97], v[244:247], v[22:37]
	s_waitcnt lgkmcnt(0)
	v_mfma_f32_32x32x16_bf16 v[6:21], v[94:97], v[74:77], v[6:21]
	s_and_saveexec_b64 s[10:11], vcc
	s_xor_b64 s[10:11], exec, s[10:11]
	v_add_u32_e32 v236, 2, v236
	s_or_saveexec_b64 s[14:15], s[10:11]
	v_add_f32_e32 v2, v2, v3
	v_add_f32_e32 v219, v219, v2
	s_xor_b64 exec, exec, s[14:15]
	s_cbranch_execz .LBB0_936
	s_and_b32 s29, s60, 0xc000
	s_add_i32 s12, s29, 0x8000
	v_add_u32_e32 v2, s12, v207
	s_waitcnt vmcnt(6)
	s_waitcnt lgkmcnt(0)
	s_barrier
	v_add_u32_e32 v3, v2, v167
	ds_read_b128 v[70:73], v3 offset:32768
	v_add_u32_e32 v3, v2, v212
	ds_read_b128 v[90:93], v3 offset:32768
	v_add_u32_e32 v3, v2, v214
	ds_read_b128 v[94:97], v3 offset:32768
	v_add_u32_e32 v3, v2, v216
	ds_read_b128 v[98:101], v3 offset:32768
	v_add_u32_e32 v3, s12, v211
	ds_read_b128 v[86:89], v3 offset:32768
	v_add_u32_e32 v3, s12, v213
	ds_read_b128 v[228:231], v3 offset:32768
	v_add_u32_e32 v3, s12, v215
	ds_read_b128 v[240:243], v3 offset:32768
	v_add_u32_e32 v3, s12, v217
	ds_read_b128 v[244:247], v3 offset:32768
	v_add_u32_e32 v3, 0x7f, v235
	v_cmp_le_i32_e64 s[10:11], s27, v3
	v_cmp_gt_i32_e32 vcc, s27, v3
	v_cmp_ge_i32_e64 s[12:13], s18, v237
	v_cvt_f32_i32_e32 v2, v237
	s_and_b64 s[10:11], s[10:11], s[12:13]
	s_min_i32 s3, s100, s101
	s_mul_i32 s98, s3, 0x218000
	s_add_i32 s32, s53, s73
	s_mov_b32 m0, s32
	v_lshl_add_u64 v[106:107], v[102:103], 0, s[98:99]
	v_lshl_add_u64 v[108:109], v[104:105], 0, s[98:99]
	global_load_lds_dwordx4 v[106:107], off
	s_add_i32 m0, s32, 0x380
	s_lshr_b32 s3, s73, 1
	s_add_i32 s3, s3, s53
	global_load_lds_dwordx4 v[106:107], off offset:128
	s_add_i32 m0, s3, 0x10000
	s_add_i32 s100, s100, 1
	s_add_i32 s53, s53, 0x4000
	global_load_lds_dwordx4 v[108:109], off
	s_and_b32 s53, s53, 0xc000
	s_cmp_eq_u64 s[10:11], 0
	s_cbranch_scc0 .Lattn_nl2
	s_waitcnt lgkmcnt(7)
	v_mfma_f32_32x32x16_bf16 v[70:85], v[70:73], v[114:117], 0
	v_cndmask_b32_e64 v3, -v189, v189, vcc
	v_sub_f32_e32 v2, v191, v2
	v_mul_f32_e64 v2, v2, -v3
	v_cvt_pk_bf16_f32 v5, v2, v3
	v_lshlrev_b32_e32 v196, 16, v5
	v_and_b32_e32 v197, 0xffff0000, v5
	s_waitcnt lgkmcnt(6)
	v_mfma_f32_32x32x16_bf16 v[70:85], v[90:93], v[118:121], v[70:85]
	v_pk_add_f32 v[2:3], v[2:3], v[196:197] neg_lo:[0,1] neg_hi:[0,1]
	s_nop 0
	v_cvt_pk_bf16_f32 v2, v2, v3
	v_and_b32_e32 v3, 0xffff, v5
	v_lshl_or_b32 v183, v2, 16, v3
	s_waitcnt lgkmcnt(5)
	v_mfma_f32_32x32x16_bf16 v[70:85], v[94:97], v[122:125], v[70:85]
	v_lshrrev_b32_e32 v3, 16, v5
	v_and_or_b32 v2, v2, s28, v3
	v_cndmask_b32_e64 v3, 0, v2, s[4:5]
	v_cndmask_b32_e64 v2, 0, v183, s[4:5]
	v_mov_b32_e32 v5, v4
	s_waitcnt lgkmcnt(4)
	v_mfma_f32_32x32x16_bf16 v[70:85], v[98:101], v[126:129], v[70:85]
	s_waitcnt lgkmcnt(3)
	v_mfma_f32_32x32x16_bf16 v[86:101], v[86:89], v[114:117], 0
	s_waitcnt lgkmcnt(2)
	v_mfma_f32_32x32x16_bf16 v[86:101], v[228:231], v[118:121], v[86:101]
	s_waitcnt lgkmcnt(1)
	v_mfma_f32_32x32x16_bf16 v[86:101], v[240:243], v[122:125], v[86:101]
	s_waitcnt lgkmcnt(0)
	v_mfma_f32_32x32x16_bf16 v[86:101], v[244:247], v[126:129], v[86:101]
	v_mfma_f32_32x32x16_bf16 v[70:85], v[110:113], v[2:5], v[70:85]
	v_mfma_f32_32x32x16_bf16 v[86:101], v[176:179], v[2:5], v[86:101]
	s_branch .Lattn_exp2
.Lattn_nl2:
	s_waitcnt lgkmcnt(7)
	v_mfma_f32_32x32x16_bf16 v[70:85], v[70:73], v[114:117], 0
	s_waitcnt lgkmcnt(6)
	v_mfma_f32_32x32x16_bf16 v[70:85], v[90:93], v[118:121], v[70:85]
	s_waitcnt lgkmcnt(5)
	v_mfma_f32_32x32x16_bf16 v[70:85], v[94:97], v[122:125], v[70:85]
	s_waitcnt lgkmcnt(4)
	v_mfma_f32_32x32x16_bf16 v[70:85], v[98:101], v[126:129], v[70:85]
	s_waitcnt lgkmcnt(3)
	v_mfma_f32_32x32x16_bf16 v[86:101], v[86:89], v[114:117], 0
	s_waitcnt lgkmcnt(2)
	v_mfma_f32_32x32x16_bf16 v[86:101], v[228:231], v[118:121], v[86:101]
	s_waitcnt lgkmcnt(1)
	v_mfma_f32_32x32x16_bf16 v[86:101], v[240:243], v[122:125], v[86:101]
	s_waitcnt lgkmcnt(0)
	v_mfma_f32_32x32x16_bf16 v[86:101], v[244:247], v[126:129], v[86:101]
	s_and_saveexec_b64 s[12:13], s[10:11]
	s_xor_b64 s[10:11], exec, s[12:13]
	s_cbranch_execz .LBB0_950
	v_sub_f32_e32 v2, v190, v2
	s_mov_b32 s12, -2.0
	v_add_f32_e32 v3, -1.0, v2
	s_mov_b32 s13, 0xc0400000
	v_pk_add_f32 v[196:197], v[2:3], s[12:13] op_sel_hi:[0,1]
	v_pk_add_f32 v[228:229], v[2:3], s[62:63] op_sel_hi:[0,1]
	v_pk_add_f32 v[230:231], v[2:3], s[74:75] op_sel_hi:[0,1]
	v_pk_add_f32 v[236:237], v[2:3], s[82:83] op_sel_hi:[0,1]
	v_pk_add_f32 v[240:241], v[2:3], s[94:95] op_sel_hi:[0,1]
	v_pk_add_f32 v[242:243], v[2:3], s[24:25] op_sel_hi:[0,1]
	v_pk_add_f32 v[244:245], v[2:3], s[56:57] op_sel_hi:[0,1]
	s_mov_b32 s12, 0xc2000000
	v_and_b32_e32 v197, 0x7fffffff, v197
	v_and_b32_e32 v196, 0x7fffffff, v196
	v_and_b32_e32 v229, 0x7fffffff, v229
	v_and_b32_e32 v228, 0x7fffffff, v228
	v_and_b32_e32 v231, 0x7fffffff, v231
	v_and_b32_e32 v230, 0x7fffffff, v230
	v_and_b32_e32 v237, 0x7fffffff, v237
	v_and_b32_e32 v236, 0x7fffffff, v236
	v_and_b32_e32 v241, 0x7fffffff, v241
	v_and_b32_e32 v240, 0x7fffffff, v240
	v_and_b32_e32 v243, 0x7fffffff, v243
	v_and_b32_e32 v242, 0x7fffffff, v242
	v_and_b32_e32 v245, 0x7fffffff, v245
	v_and_b32_e32 v244, 0x7fffffff, v244
	v_mov_b32_e32 v183, v182
	s_mov_b32 s13, 0xc2040000
	v_and_b32_e32 v246, 0x7fffffff, v2
	v_and_b32_e32 v247, 0x7fffffff, v3
	v_pk_fma_f32 v[84:85], v[182:183], v[244:245], v[84:85]
	v_pk_fma_f32 v[82:83], v[182:183], v[242:243], v[82:83]
	v_pk_fma_f32 v[80:81], v[182:183], v[240:241], v[80:81]
	v_pk_fma_f32 v[78:79], v[182:183], v[236:237], v[78:79]
	v_pk_fma_f32 v[76:77], v[182:183], v[230:231], v[76:77]
	v_pk_fma_f32 v[74:75], v[182:183], v[228:229], v[74:75]
	v_pk_fma_f32 v[72:73], v[182:183], v[196:197], v[72:73]
	v_pk_add_f32 v[196:197], v[2:3], s[58:59] op_sel_hi:[0,1]
	v_pk_add_f32 v[228:229], v[2:3], s[0:1] op_sel_hi:[0,1]
	v_pk_add_f32 v[230:231], v[2:3], s[20:21] op_sel_hi:[0,1]
	v_pk_add_f32 v[236:237], v[2:3], s[86:87] op_sel_hi:[0,1]
	v_pk_add_f32 v[240:241], v[2:3], s[78:79] op_sel_hi:[0,1]
	v_pk_add_f32 v[242:243], v[2:3], s[66:67] op_sel_hi:[0,1]
	v_pk_add_f32 v[244:245], v[2:3], s[54:55] op_sel_hi:[0,1]
	v_pk_add_f32 v[2:3], v[2:3], s[12:13] op_sel_hi:[0,1]
	v_and_b32_e32 v3, 0x7fffffff, v3
	v_and_b32_e32 v2, 0x7fffffff, v2
	v_and_b32_e32 v245, 0x7fffffff, v245
	v_and_b32_e32 v244, 0x7fffffff, v244
	v_and_b32_e32 v243, 0x7fffffff, v243
	v_and_b32_e32 v242, 0x7fffffff, v242
	v_and_b32_e32 v241, 0x7fffffff, v241
	v_and_b32_e32 v240, 0x7fffffff, v240
	v_and_b32_e32 v237, 0x7fffffff, v237
	v_and_b32_e32 v236, 0x7fffffff, v236
	v_and_b32_e32 v231, 0x7fffffff, v231
	v_and_b32_e32 v230, 0x7fffffff, v230
	v_and_b32_e32 v229, 0x7fffffff, v229
	v_and_b32_e32 v228, 0x7fffffff, v228
	v_and_b32_e32 v197, 0x7fffffff, v197
	v_and_b32_e32 v196, 0x7fffffff, v196
	v_pk_fma_f32 v[70:71], v[184:185], v[246:247], v[70:71]
	v_pk_fma_f32 v[100:101], v[182:183], v[196:197], v[100:101]
	v_pk_fma_f32 v[98:99], v[182:183], v[228:229], v[98:99]
	v_pk_fma_f32 v[96:97], v[182:183], v[230:231], v[96:97]
	v_pk_fma_f32 v[94:95], v[182:183], v[236:237], v[94:95]
	v_pk_fma_f32 v[92:93], v[182:183], v[240:241], v[92:93]
	v_pk_fma_f32 v[90:91], v[182:183], v[242:243], v[90:91]
	v_pk_fma_f32 v[88:89], v[182:183], v[244:245], v[88:89]
	v_pk_fma_f32 v[86:87], v[184:185], v[2:3], v[86:87]
